# inproj na_v tiles rewritten by hand: 128 rows x two n-tiles sharing the H tile, 3-stage 24KB LDS ring, batched transposed epilogue; 528 items instead of 1056
# speedup vs baseline: 1.1040x; 1.0033x over previous
.LBB0_443:
	v_readlane_b32 s16, v225, 42
	v_readlane_b32 s17, v225, 43
	s_load_dword s2, s[16:17], 0x0
	s_waitcnt lgkmcnt(0)
	s_add_i32 s42, s2, s42
	s_cmpk_gt_i32 s42, 0xbdb
	s_cbranch_scc1 .LBB0_473
.LBB0_444:
	s_cmpk_gt_i32 s42, 0x9cb
	s_mov_b64 s[16:17], -1
	s_cbranch_scc0 .LBB0_452
	s_sub_i32 s2, s42, 0x9cc
	s_lshr_b32 s26, s2, 1
	s_and_b32 s27, s2, 1
	s_lshl_b32 s26, s26, 7
	s_lshl_b32 s2, s26, 11
	s_add_u32 s16, s36, s2
	s_addc_u32 s17, s37, 0
	s_lshl_b32 s2, s27, 19
	s_add_u32 s18, s59, s2
	v_readlane_b32 s19, v225, 54
	s_addc_u32 s19, s19, 0
	s_add_u32 s18, s18, 0x200000
	s_addc_u32 s19, s19, 0
	s_add_u32 s20, s18, 0x40000
	s_addc_u32 s21, s19, 0
	s_cmp_lt_u32 s26, 0x8000
	s_cbranch_scc0 .Lnv_ctx
	s_lshr_b32 s2, s26, 13
	s_and_b32 s100, s26, 0x1fff
	s_add_i32 s100, s100, 0x100
	s_branch .Lnv_ri
.Lnv_ctx:
	s_sub_i32 s100, s26, 0x8000
	s_lshr_b32 s2, s100, 8
	s_and_b32 s100, s100, 0xff
.Lnv_ri:
	s_mul_i32 s2, s2, 0x840000
	s_lshl_b32 s100, s100, 1
	s_add_i32 s26, s2, s100
	s_mul_i32 s2, s27, 0x420000
	s_add_i32 s26, s26, s2
	s_movk_i32 s2, 0x1320
	v_lshrrev_b32_e32 v0, 2, v196
	v_and_b32_e32 v0, 12, v0
	v_lshrrev_b32_e64 v0, v0, s2
	v_xor_b32_e32 v0, v0, v196
	v_and_b32_e32 v0, 3, v0
	v_lshlrev_b32_e32 v0, 4, v0
	v_lshrrev_b32_e32 v2, 2, v196
	v_lshl_add_u32 v2, v2, 11, v0
	v_add_u32_e32 v3, 0x20000, v2
	v_and_b32_e32 v214, 15, v196
	v_and_b32_e32 v215, 12, v214
	v_lshrrev_b32_e64 v215, v215, s2
	v_and_b32_e32 v215, 3, v215
	v_bfe_u32 v220, v196, 4, 2
	v_xor_b32_e32 v215, v215, v220
	v_lshlrev_b32_e32 v215, 4, v215
	v_lshl_add_u32 v215, v214, 6, v215
	v_lshrrev_b32_e32 v214, 7, v196
	v_lshl_add_u32 v124, v214, 12, v215
	v_bfe_u32 v214, v196, 6, 1
	v_lshl_add_u32 v126, v214, 12, v215
	v_add_u32_e32 v127, 0xc000, v124
	v_add_u32_e32 v144, 0xc000, v126
	v_readfirstlane_b32 s22, v196
	s_lshl_b32 s22, s22, 4
	s_mov_b32 m0, s22
	s_nop 0
	global_load_lds_dwordx4 v2, s[16:17]
	s_add_i32 m0, s22, 0x1000
	s_nop 0
	global_load_lds_dwordx4 v3, s[16:17]
	s_add_i32 m0, s22, 0x2000
	s_nop 0
	global_load_lds_dwordx4 v2, s[18:19]
	s_add_i32 m0, s22, 0x3000
	s_nop 0
	global_load_lds_dwordx4 v3, s[18:19]
	s_add_i32 m0, s22, 0x4000
	s_nop 0
	global_load_lds_dwordx4 v2, s[20:21]
	s_add_i32 m0, s22, 0x5000
	s_nop 0
	global_load_lds_dwordx4 v3, s[20:21]
	v_add_u32_e32 v2, 64, v2
	v_add_u32_e32 v3, 64, v3
	s_add_i32 m0, s22, 0x6000
	s_nop 0
	global_load_lds_dwordx4 v2, s[16:17]
	s_add_i32 m0, s22, 0x7000
	s_nop 0
	global_load_lds_dwordx4 v3, s[16:17]
	s_add_i32 m0, s22, 0x8000
	s_nop 0
	global_load_lds_dwordx4 v2, s[18:19]
	s_add_i32 m0, s22, 0x9000
	s_nop 0
	global_load_lds_dwordx4 v3, s[18:19]
	s_add_i32 m0, s22, 0xa000
	s_nop 0
	global_load_lds_dwordx4 v2, s[20:21]
	s_add_i32 m0, s22, 0xb000
	s_nop 0
	global_load_lds_dwordx4 v3, s[20:21]
	v_add_u32_e32 v2, 64, v2
	v_add_u32_e32 v3, 64, v3
	v_mov_b32_e32 v4, 0
	v_mov_b32_e32 v5, 0
	v_mov_b32_e32 v6, 0
	v_mov_b32_e32 v7, 0
	v_mov_b32_e32 v8, 0
	v_mov_b32_e32 v9, 0
	v_mov_b32_e32 v10, 0
	v_mov_b32_e32 v11, 0
	v_mov_b32_e32 v12, 0
	v_mov_b32_e32 v13, 0
	v_mov_b32_e32 v14, 0
	v_mov_b32_e32 v15, 0
	v_mov_b32_e32 v16, 0
	v_mov_b32_e32 v17, 0
	v_mov_b32_e32 v18, 0
	v_mov_b32_e32 v19, 0
	v_mov_b32_e32 v20, 0
	v_mov_b32_e32 v21, 0
	v_mov_b32_e32 v22, 0
	v_mov_b32_e32 v23, 0
	v_mov_b32_e32 v24, 0
	v_mov_b32_e32 v25, 0
	v_mov_b32_e32 v26, 0
	v_mov_b32_e32 v27, 0
	v_mov_b32_e32 v28, 0
	v_mov_b32_e32 v29, 0
	v_mov_b32_e32 v30, 0
	v_mov_b32_e32 v31, 0
	v_mov_b32_e32 v32, 0
	v_mov_b32_e32 v33, 0
	v_mov_b32_e32 v34, 0
	v_mov_b32_e32 v35, 0
	v_mov_b32_e32 v36, 0
	v_mov_b32_e32 v37, 0
	v_mov_b32_e32 v38, 0
	v_mov_b32_e32 v39, 0
	v_mov_b32_e32 v40, 0
	v_mov_b32_e32 v41, 0
	v_mov_b32_e32 v42, 0
	v_mov_b32_e32 v43, 0
	v_mov_b32_e32 v44, 0
	v_mov_b32_e32 v45, 0
	v_mov_b32_e32 v46, 0
	v_mov_b32_e32 v47, 0
	v_mov_b32_e32 v48, 0
	v_mov_b32_e32 v49, 0
	v_mov_b32_e32 v50, 0
	v_mov_b32_e32 v51, 0
	v_mov_b32_e32 v52, 0
	v_mov_b32_e32 v53, 0
	v_mov_b32_e32 v54, 0
	v_mov_b32_e32 v55, 0
	v_mov_b32_e32 v56, 0
	v_mov_b32_e32 v57, 0
	v_mov_b32_e32 v58, 0
	v_mov_b32_e32 v59, 0
	v_mov_b32_e32 v60, 0
	v_mov_b32_e32 v61, 0
	v_mov_b32_e32 v62, 0
	v_mov_b32_e32 v63, 0
	v_mov_b32_e32 v64, 0
	v_mov_b32_e32 v65, 0
	v_mov_b32_e32 v66, 0
	v_mov_b32_e32 v67, 0
	v_mov_b32_e32 v68, 0
	v_mov_b32_e32 v69, 0
	v_mov_b32_e32 v70, 0
	v_mov_b32_e32 v71, 0
	v_mov_b32_e32 v72, 0
	v_mov_b32_e32 v73, 0
	v_mov_b32_e32 v74, 0
	v_mov_b32_e32 v75, 0
	v_mov_b32_e32 v76, 0
	v_mov_b32_e32 v77, 0
	v_mov_b32_e32 v78, 0
	v_mov_b32_e32 v79, 0
	v_mov_b32_e32 v80, 0
	v_mov_b32_e32 v81, 0
	v_mov_b32_e32 v82, 0
	v_mov_b32_e32 v83, 0
	v_mov_b32_e32 v84, 0
	v_mov_b32_e32 v85, 0
	v_mov_b32_e32 v86, 0
	v_mov_b32_e32 v87, 0
	v_mov_b32_e32 v88, 0
	v_mov_b32_e32 v89, 0
	v_mov_b32_e32 v90, 0
	v_mov_b32_e32 v91, 0
	v_mov_b32_e32 v92, 0
	v_mov_b32_e32 v93, 0
	v_mov_b32_e32 v94, 0
	v_mov_b32_e32 v95, 0
	v_mov_b32_e32 v96, 0
	v_mov_b32_e32 v97, 0
	v_mov_b32_e32 v98, 0
	v_mov_b32_e32 v99, 0
	v_mov_b32_e32 v100, 0
	v_mov_b32_e32 v101, 0
	v_mov_b32_e32 v102, 0
	v_mov_b32_e32 v103, 0
	v_mov_b32_e32 v104, 0
	v_mov_b32_e32 v105, 0
	v_mov_b32_e32 v106, 0
	v_mov_b32_e32 v107, 0
	v_mov_b32_e32 v108, 0
	v_mov_b32_e32 v109, 0
	v_mov_b32_e32 v110, 0
	v_mov_b32_e32 v111, 0
	v_mov_b32_e32 v112, 0
	v_mov_b32_e32 v113, 0
	v_mov_b32_e32 v114, 0
	v_mov_b32_e32 v115, 0
	v_mov_b32_e32 v116, 0
	v_mov_b32_e32 v117, 0
	v_mov_b32_e32 v118, 0
	v_mov_b32_e32 v119, 0
	v_mov_b32_e32 v120, 0
	v_mov_b32_e32 v121, 0
	v_mov_b32_e32 v122, 0
	v_mov_b32_e32 v123, 0
	v_mov_b32_e32 v128, 0
	v_mov_b32_e32 v129, 0
	v_mov_b32_e32 v130, 0
	v_mov_b32_e32 v131, 0
	v_mov_b32_e32 v132, 0
	v_mov_b32_e32 v133, 0
	v_mov_b32_e32 v134, 0
	v_mov_b32_e32 v135, 0
	s_mov_b32 s23, 10
.Lnv_loop:
	s_waitcnt vmcnt(6)
	s_barrier
	s_add_i32 m0, s22, 0xc000
	s_nop 0
	global_load_lds_dwordx4 v2, s[16:17]
	s_add_i32 m0, s22, 0xd000
	s_nop 0
	global_load_lds_dwordx4 v3, s[16:17]
	s_add_i32 m0, s22, 0xe000
	s_nop 0
	global_load_lds_dwordx4 v2, s[18:19]
	s_add_i32 m0, s22, 0xf000
	s_nop 0
	global_load_lds_dwordx4 v3, s[18:19]
	s_add_i32 m0, s22, 0x10000
	s_nop 0
	global_load_lds_dwordx4 v2, s[20:21]
	s_add_i32 m0, s22, 0x11000
	s_nop 0
	global_load_lds_dwordx4 v3, s[20:21]
	v_add_u32_e32 v2, 64, v2
	v_add_u32_e32 v3, 64, v3
	ds_read_b128 v[136:139], v124 offset:0
	ds_read_b128 v[140:143], v124 offset:1024
	ds_read_b128 v[216:219], v124 offset:2048
	ds_read_b128 v[228:231], v124 offset:3072
	ds_read_b128 v[232:235], v126 offset:8192
	ds_read_b128 v[236:239], v126 offset:9216
	ds_read_b128 v[240:243], v126 offset:10240
	ds_read_b128 v[244:247], v126 offset:11264
	s_waitcnt lgkmcnt(3)
	s_setprio 1
	v_mfma_f32_16x16x32_bf16 v[4:7], v[136:139], v[232:235], v[4:7]
	v_mfma_f32_16x16x32_bf16 v[20:23], v[140:143], v[232:235], v[20:23]
	v_mfma_f32_16x16x32_bf16 v[36:39], v[216:219], v[232:235], v[36:39]
	v_mfma_f32_16x16x32_bf16 v[52:55], v[228:231], v[232:235], v[52:55]
	s_setprio 0
	ds_read_b128 v[232:235], v126 offset:16384
	s_waitcnt lgkmcnt(3)
	s_setprio 1
	v_mfma_f32_16x16x32_bf16 v[8:11], v[136:139], v[236:239], v[8:11]
	v_mfma_f32_16x16x32_bf16 v[24:27], v[140:143], v[236:239], v[24:27]
	v_mfma_f32_16x16x32_bf16 v[40:43], v[216:219], v[236:239], v[40:43]
	v_mfma_f32_16x16x32_bf16 v[56:59], v[228:231], v[236:239], v[56:59]
	s_setprio 0
	ds_read_b128 v[236:239], v126 offset:17408
	s_waitcnt lgkmcnt(3)
	s_setprio 1
	v_mfma_f32_16x16x32_bf16 v[12:15], v[136:139], v[240:243], v[12:15]
	v_mfma_f32_16x16x32_bf16 v[28:31], v[140:143], v[240:243], v[28:31]
	v_mfma_f32_16x16x32_bf16 v[44:47], v[216:219], v[240:243], v[44:47]
	v_mfma_f32_16x16x32_bf16 v[60:63], v[228:231], v[240:243], v[60:63]
	s_setprio 0
	ds_read_b128 v[240:243], v126 offset:18432
	s_waitcnt lgkmcnt(3)
	s_setprio 1
	v_mfma_f32_16x16x32_bf16 v[16:19], v[136:139], v[244:247], v[16:19]
	v_mfma_f32_16x16x32_bf16 v[32:35], v[140:143], v[244:247], v[32:35]
	v_mfma_f32_16x16x32_bf16 v[48:51], v[216:219], v[244:247], v[48:51]
	v_mfma_f32_16x16x32_bf16 v[64:67], v[228:231], v[244:247], v[64:67]
	s_setprio 0
	ds_read_b128 v[244:247], v126 offset:19456
	s_waitcnt lgkmcnt(3)
	s_setprio 1
	v_mfma_f32_16x16x32_bf16 v[68:71], v[136:139], v[232:235], v[68:71]
	v_mfma_f32_16x16x32_bf16 v[84:87], v[140:143], v[232:235], v[84:87]
	v_mfma_f32_16x16x32_bf16 v[100:103], v[216:219], v[232:235], v[100:103]
	v_mfma_f32_16x16x32_bf16 v[116:119], v[228:231], v[232:235], v[116:119]
	s_setprio 0
	s_waitcnt lgkmcnt(2)
	s_setprio 1
	v_mfma_f32_16x16x32_bf16 v[72:75], v[136:139], v[236:239], v[72:75]
	v_mfma_f32_16x16x32_bf16 v[88:91], v[140:143], v[236:239], v[88:91]
	v_mfma_f32_16x16x32_bf16 v[104:107], v[216:219], v[236:239], v[104:107]
	v_mfma_f32_16x16x32_bf16 v[120:123], v[228:231], v[236:239], v[120:123]
	s_setprio 0
	s_waitcnt lgkmcnt(1)
	s_setprio 1
	v_mfma_f32_16x16x32_bf16 v[76:79], v[136:139], v[240:243], v[76:79]
	v_mfma_f32_16x16x32_bf16 v[92:95], v[140:143], v[240:243], v[92:95]
	v_mfma_f32_16x16x32_bf16 v[108:111], v[216:219], v[240:243], v[108:111]
	v_mfma_f32_16x16x32_bf16 v[128:131], v[228:231], v[240:243], v[128:131]
	s_setprio 0
	s_waitcnt lgkmcnt(0)
	s_setprio 1
	v_mfma_f32_16x16x32_bf16 v[80:83], v[136:139], v[244:247], v[80:83]
	v_mfma_f32_16x16x32_bf16 v[96:99], v[140:143], v[244:247], v[96:99]
	v_mfma_f32_16x16x32_bf16 v[112:115], v[216:219], v[244:247], v[112:115]
	v_mfma_f32_16x16x32_bf16 v[132:135], v[228:231], v[244:247], v[132:135]
	s_setprio 0
	s_waitcnt vmcnt(6)
	s_barrier
	s_mov_b32 m0, s22
	s_nop 0
	global_load_lds_dwordx4 v2, s[16:17]
	s_add_i32 m0, s22, 0x1000
	s_nop 0
	global_load_lds_dwordx4 v3, s[16:17]
	s_add_i32 m0, s22, 0x2000
	s_nop 0
	global_load_lds_dwordx4 v2, s[18:19]
	s_add_i32 m0, s22, 0x3000
	s_nop 0
	global_load_lds_dwordx4 v3, s[18:19]
	s_add_i32 m0, s22, 0x4000
	s_nop 0
	global_load_lds_dwordx4 v2, s[20:21]
	s_add_i32 m0, s22, 0x5000
	s_nop 0
	global_load_lds_dwordx4 v3, s[20:21]
	v_add_u32_e32 v2, 64, v2
	v_add_u32_e32 v3, 64, v3
	ds_read_b128 v[136:139], v124 offset:24576
	ds_read_b128 v[140:143], v124 offset:25600
	ds_read_b128 v[216:219], v124 offset:26624
	ds_read_b128 v[228:231], v124 offset:27648
	ds_read_b128 v[232:235], v126 offset:32768
	ds_read_b128 v[236:239], v126 offset:33792
	ds_read_b128 v[240:243], v126 offset:34816
	ds_read_b128 v[244:247], v126 offset:35840
	s_waitcnt lgkmcnt(3)
	s_setprio 1
	v_mfma_f32_16x16x32_bf16 v[4:7], v[136:139], v[232:235], v[4:7]
	v_mfma_f32_16x16x32_bf16 v[20:23], v[140:143], v[232:235], v[20:23]
	v_mfma_f32_16x16x32_bf16 v[36:39], v[216:219], v[232:235], v[36:39]
	v_mfma_f32_16x16x32_bf16 v[52:55], v[228:231], v[232:235], v[52:55]
	s_setprio 0
	ds_read_b128 v[232:235], v126 offset:40960
	s_waitcnt lgkmcnt(3)
	s_setprio 1
	v_mfma_f32_16x16x32_bf16 v[8:11], v[136:139], v[236:239], v[8:11]
	v_mfma_f32_16x16x32_bf16 v[24:27], v[140:143], v[236:239], v[24:27]
	v_mfma_f32_16x16x32_bf16 v[40:43], v[216:219], v[236:239], v[40:43]
	v_mfma_f32_16x16x32_bf16 v[56:59], v[228:231], v[236:239], v[56:59]
	s_setprio 0
	ds_read_b128 v[236:239], v126 offset:41984
	s_waitcnt lgkmcnt(3)
	s_setprio 1
	v_mfma_f32_16x16x32_bf16 v[12:15], v[136:139], v[240:243], v[12:15]
	v_mfma_f32_16x16x32_bf16 v[28:31], v[140:143], v[240:243], v[28:31]
	v_mfma_f32_16x16x32_bf16 v[44:47], v[216:219], v[240:243], v[44:47]
	v_mfma_f32_16x16x32_bf16 v[60:63], v[228:231], v[240:243], v[60:63]
	s_setprio 0
	ds_read_b128 v[240:243], v126 offset:43008
	s_waitcnt lgkmcnt(3)
	s_setprio 1
	v_mfma_f32_16x16x32_bf16 v[16:19], v[136:139], v[244:247], v[16:19]
	v_mfma_f32_16x16x32_bf16 v[32:35], v[140:143], v[244:247], v[32:35]
	v_mfma_f32_16x16x32_bf16 v[48:51], v[216:219], v[244:247], v[48:51]
	v_mfma_f32_16x16x32_bf16 v[64:67], v[228:231], v[244:247], v[64:67]
	s_setprio 0
	ds_read_b128 v[244:247], v126 offset:44032
	s_waitcnt lgkmcnt(3)
	s_setprio 1
	v_mfma_f32_16x16x32_bf16 v[68:71], v[136:139], v[232:235], v[68:71]
	v_mfma_f32_16x16x32_bf16 v[84:87], v[140:143], v[232:235], v[84:87]
	v_mfma_f32_16x16x32_bf16 v[100:103], v[216:219], v[232:235], v[100:103]
	v_mfma_f32_16x16x32_bf16 v[116:119], v[228:231], v[232:235], v[116:119]
	s_setprio 0
	s_waitcnt lgkmcnt(2)
	s_setprio 1
	v_mfma_f32_16x16x32_bf16 v[72:75], v[136:139], v[236:239], v[72:75]
	v_mfma_f32_16x16x32_bf16 v[88:91], v[140:143], v[236:239], v[88:91]
	v_mfma_f32_16x16x32_bf16 v[104:107], v[216:219], v[236:239], v[104:107]
	v_mfma_f32_16x16x32_bf16 v[120:123], v[228:231], v[236:239], v[120:123]
	s_setprio 0
	s_waitcnt lgkmcnt(1)
	s_setprio 1
	v_mfma_f32_16x16x32_bf16 v[76:79], v[136:139], v[240:243], v[76:79]
	v_mfma_f32_16x16x32_bf16 v[92:95], v[140:143], v[240:243], v[92:95]
	v_mfma_f32_16x16x32_bf16 v[108:111], v[216:219], v[240:243], v[108:111]
	v_mfma_f32_16x16x32_bf16 v[128:131], v[228:231], v[240:243], v[128:131]
	s_setprio 0
	s_waitcnt lgkmcnt(0)
	s_setprio 1
	v_mfma_f32_16x16x32_bf16 v[80:83], v[136:139], v[244:247], v[80:83]
	v_mfma_f32_16x16x32_bf16 v[96:99], v[140:143], v[244:247], v[96:99]
	v_mfma_f32_16x16x32_bf16 v[112:115], v[216:219], v[244:247], v[112:115]
	v_mfma_f32_16x16x32_bf16 v[132:135], v[228:231], v[244:247], v[132:135]
	s_setprio 0
	s_waitcnt vmcnt(6)
	s_barrier
	s_add_i32 m0, s22, 0x6000
	s_nop 0
	global_load_lds_dwordx4 v2, s[16:17]
	s_add_i32 m0, s22, 0x7000
	s_nop 0
	global_load_lds_dwordx4 v3, s[16:17]
	s_add_i32 m0, s22, 0x8000
	s_nop 0
	global_load_lds_dwordx4 v2, s[18:19]
	s_add_i32 m0, s22, 0x9000
	s_nop 0
	global_load_lds_dwordx4 v3, s[18:19]
	s_add_i32 m0, s22, 0xa000
	s_nop 0
	global_load_lds_dwordx4 v2, s[20:21]
	s_add_i32 m0, s22, 0xb000
	s_nop 0
	global_load_lds_dwordx4 v3, s[20:21]
	v_add_u32_e32 v2, 64, v2
	v_add_u32_e32 v3, 64, v3
	ds_read_b128 v[136:139], v127 offset:0
	ds_read_b128 v[140:143], v127 offset:1024
	ds_read_b128 v[216:219], v127 offset:2048
	ds_read_b128 v[228:231], v127 offset:3072
	ds_read_b128 v[232:235], v144 offset:8192
	ds_read_b128 v[236:239], v144 offset:9216
	ds_read_b128 v[240:243], v144 offset:10240
	ds_read_b128 v[244:247], v144 offset:11264
	s_waitcnt lgkmcnt(3)
	s_setprio 1
	v_mfma_f32_16x16x32_bf16 v[4:7], v[136:139], v[232:235], v[4:7]
	v_mfma_f32_16x16x32_bf16 v[20:23], v[140:143], v[232:235], v[20:23]
	v_mfma_f32_16x16x32_bf16 v[36:39], v[216:219], v[232:235], v[36:39]
	v_mfma_f32_16x16x32_bf16 v[52:55], v[228:231], v[232:235], v[52:55]
	s_setprio 0
	ds_read_b128 v[232:235], v144 offset:16384
	s_waitcnt lgkmcnt(3)
	s_setprio 1
	v_mfma_f32_16x16x32_bf16 v[8:11], v[136:139], v[236:239], v[8:11]
	v_mfma_f32_16x16x32_bf16 v[24:27], v[140:143], v[236:239], v[24:27]
	v_mfma_f32_16x16x32_bf16 v[40:43], v[216:219], v[236:239], v[40:43]
	v_mfma_f32_16x16x32_bf16 v[56:59], v[228:231], v[236:239], v[56:59]
	s_setprio 0
	ds_read_b128 v[236:239], v144 offset:17408
	s_waitcnt lgkmcnt(3)
	s_setprio 1
	v_mfma_f32_16x16x32_bf16 v[12:15], v[136:139], v[240:243], v[12:15]
	v_mfma_f32_16x16x32_bf16 v[28:31], v[140:143], v[240:243], v[28:31]
	v_mfma_f32_16x16x32_bf16 v[44:47], v[216:219], v[240:243], v[44:47]
	v_mfma_f32_16x16x32_bf16 v[60:63], v[228:231], v[240:243], v[60:63]
	s_setprio 0
	ds_read_b128 v[240:243], v144 offset:18432
	s_waitcnt lgkmcnt(3)
	s_setprio 1
	v_mfma_f32_16x16x32_bf16 v[16:19], v[136:139], v[244:247], v[16:19]
	v_mfma_f32_16x16x32_bf16 v[32:35], v[140:143], v[244:247], v[32:35]
	v_mfma_f32_16x16x32_bf16 v[48:51], v[216:219], v[244:247], v[48:51]
	v_mfma_f32_16x16x32_bf16 v[64:67], v[228:231], v[244:247], v[64:67]
	s_setprio 0
	ds_read_b128 v[244:247], v144 offset:19456
	s_waitcnt lgkmcnt(3)
	s_setprio 1
	v_mfma_f32_16x16x32_bf16 v[68:71], v[136:139], v[232:235], v[68:71]
	v_mfma_f32_16x16x32_bf16 v[84:87], v[140:143], v[232:235], v[84:87]
	v_mfma_f32_16x16x32_bf16 v[100:103], v[216:219], v[232:235], v[100:103]
	v_mfma_f32_16x16x32_bf16 v[116:119], v[228:231], v[232:235], v[116:119]
	s_setprio 0
	s_waitcnt lgkmcnt(2)
	s_setprio 1
	v_mfma_f32_16x16x32_bf16 v[72:75], v[136:139], v[236:239], v[72:75]
	v_mfma_f32_16x16x32_bf16 v[88:91], v[140:143], v[236:239], v[88:91]
	v_mfma_f32_16x16x32_bf16 v[104:107], v[216:219], v[236:239], v[104:107]
	v_mfma_f32_16x16x32_bf16 v[120:123], v[228:231], v[236:239], v[120:123]
	s_setprio 0
	s_waitcnt lgkmcnt(1)
	s_setprio 1
	v_mfma_f32_16x16x32_bf16 v[76:79], v[136:139], v[240:243], v[76:79]
	v_mfma_f32_16x16x32_bf16 v[92:95], v[140:143], v[240:243], v[92:95]
	v_mfma_f32_16x16x32_bf16 v[108:111], v[216:219], v[240:243], v[108:111]
	v_mfma_f32_16x16x32_bf16 v[128:131], v[228:231], v[240:243], v[128:131]
	s_setprio 0
	s_waitcnt lgkmcnt(0)
	s_setprio 1
	v_mfma_f32_16x16x32_bf16 v[80:83], v[136:139], v[244:247], v[80:83]
	v_mfma_f32_16x16x32_bf16 v[96:99], v[140:143], v[244:247], v[96:99]
	v_mfma_f32_16x16x32_bf16 v[112:115], v[216:219], v[244:247], v[112:115]
	v_mfma_f32_16x16x32_bf16 v[132:135], v[228:231], v[244:247], v[132:135]
	s_setprio 0
	s_sub_u32 s23, s23, 1
	s_cmp_lg_u32 s23, 0
	s_cbranch_scc1 .Lnv_loop
	s_waitcnt vmcnt(6)
	s_barrier
	ds_read_b128 v[136:139], v124 offset:0
	ds_read_b128 v[140:143], v124 offset:1024
	ds_read_b128 v[216:219], v124 offset:2048
	ds_read_b128 v[228:231], v124 offset:3072
	ds_read_b128 v[232:235], v126 offset:8192
	ds_read_b128 v[236:239], v126 offset:9216
	ds_read_b128 v[240:243], v126 offset:10240
	ds_read_b128 v[244:247], v126 offset:11264
	s_waitcnt lgkmcnt(3)
	s_setprio 1
	v_mfma_f32_16x16x32_bf16 v[4:7], v[136:139], v[232:235], v[4:7]
	v_mfma_f32_16x16x32_bf16 v[20:23], v[140:143], v[232:235], v[20:23]
	v_mfma_f32_16x16x32_bf16 v[36:39], v[216:219], v[232:235], v[36:39]
	v_mfma_f32_16x16x32_bf16 v[52:55], v[228:231], v[232:235], v[52:55]
	s_setprio 0
	ds_read_b128 v[232:235], v126 offset:16384
	s_waitcnt lgkmcnt(3)
	s_setprio 1
	v_mfma_f32_16x16x32_bf16 v[8:11], v[136:139], v[236:239], v[8:11]
	v_mfma_f32_16x16x32_bf16 v[24:27], v[140:143], v[236:239], v[24:27]
	v_mfma_f32_16x16x32_bf16 v[40:43], v[216:219], v[236:239], v[40:43]
	v_mfma_f32_16x16x32_bf16 v[56:59], v[228:231], v[236:239], v[56:59]
	s_setprio 0
	ds_read_b128 v[236:239], v126 offset:17408
	s_waitcnt lgkmcnt(3)
	s_setprio 1
	v_mfma_f32_16x16x32_bf16 v[12:15], v[136:139], v[240:243], v[12:15]
	v_mfma_f32_16x16x32_bf16 v[28:31], v[140:143], v[240:243], v[28:31]
	v_mfma_f32_16x16x32_bf16 v[44:47], v[216:219], v[240:243], v[44:47]
	v_mfma_f32_16x16x32_bf16 v[60:63], v[228:231], v[240:243], v[60:63]
	s_setprio 0
	ds_read_b128 v[240:243], v126 offset:18432
	s_waitcnt lgkmcnt(3)
	s_setprio 1
	v_mfma_f32_16x16x32_bf16 v[16:19], v[136:139], v[244:247], v[16:19]
	v_mfma_f32_16x16x32_bf16 v[32:35], v[140:143], v[244:247], v[32:35]
	v_mfma_f32_16x16x32_bf16 v[48:51], v[216:219], v[244:247], v[48:51]
	v_mfma_f32_16x16x32_bf16 v[64:67], v[228:231], v[244:247], v[64:67]
	s_setprio 0
	ds_read_b128 v[244:247], v126 offset:19456
	s_waitcnt lgkmcnt(3)
	s_setprio 1
	v_mfma_f32_16x16x32_bf16 v[68:71], v[136:139], v[232:235], v[68:71]
	v_mfma_f32_16x16x32_bf16 v[84:87], v[140:143], v[232:235], v[84:87]
	v_mfma_f32_16x16x32_bf16 v[100:103], v[216:219], v[232:235], v[100:103]
	v_mfma_f32_16x16x32_bf16 v[116:119], v[228:231], v[232:235], v[116:119]
	s_setprio 0
	s_waitcnt lgkmcnt(2)
	s_setprio 1
	v_mfma_f32_16x16x32_bf16 v[72:75], v[136:139], v[236:239], v[72:75]
	v_mfma_f32_16x16x32_bf16 v[88:91], v[140:143], v[236:239], v[88:91]
	v_mfma_f32_16x16x32_bf16 v[104:107], v[216:219], v[236:239], v[104:107]
	v_mfma_f32_16x16x32_bf16 v[120:123], v[228:231], v[236:239], v[120:123]
	s_setprio 0
	s_waitcnt lgkmcnt(1)
	s_setprio 1
	v_mfma_f32_16x16x32_bf16 v[76:79], v[136:139], v[240:243], v[76:79]
	v_mfma_f32_16x16x32_bf16 v[92:95], v[140:143], v[240:243], v[92:95]
	v_mfma_f32_16x16x32_bf16 v[108:111], v[216:219], v[240:243], v[108:111]
	v_mfma_f32_16x16x32_bf16 v[128:131], v[228:231], v[240:243], v[128:131]
	s_setprio 0
	s_waitcnt lgkmcnt(0)
	s_setprio 1
	v_mfma_f32_16x16x32_bf16 v[80:83], v[136:139], v[244:247], v[80:83]
	v_mfma_f32_16x16x32_bf16 v[96:99], v[140:143], v[244:247], v[96:99]
	v_mfma_f32_16x16x32_bf16 v[112:115], v[216:219], v[244:247], v[112:115]
	v_mfma_f32_16x16x32_bf16 v[132:135], v[228:231], v[244:247], v[132:135]
	s_setprio 0
	s_waitcnt vmcnt(0)
	s_barrier
	ds_read_b128 v[136:139], v124 offset:24576
	ds_read_b128 v[140:143], v124 offset:25600
	ds_read_b128 v[216:219], v124 offset:26624
	ds_read_b128 v[228:231], v124 offset:27648
	ds_read_b128 v[232:235], v126 offset:32768
	ds_read_b128 v[236:239], v126 offset:33792
	ds_read_b128 v[240:243], v126 offset:34816
	ds_read_b128 v[244:247], v126 offset:35840
	s_waitcnt lgkmcnt(3)
	s_setprio 1
	v_mfma_f32_16x16x32_bf16 v[4:7], v[136:139], v[232:235], v[4:7]
	v_mfma_f32_16x16x32_bf16 v[20:23], v[140:143], v[232:235], v[20:23]
	v_mfma_f32_16x16x32_bf16 v[36:39], v[216:219], v[232:235], v[36:39]
	v_mfma_f32_16x16x32_bf16 v[52:55], v[228:231], v[232:235], v[52:55]
	s_setprio 0
	ds_read_b128 v[232:235], v126 offset:40960
	s_waitcnt lgkmcnt(3)
	s_setprio 1
	v_mfma_f32_16x16x32_bf16 v[8:11], v[136:139], v[236:239], v[8:11]
	v_mfma_f32_16x16x32_bf16 v[24:27], v[140:143], v[236:239], v[24:27]
	v_mfma_f32_16x16x32_bf16 v[40:43], v[216:219], v[236:239], v[40:43]
	v_mfma_f32_16x16x32_bf16 v[56:59], v[228:231], v[236:239], v[56:59]
	s_setprio 0
	ds_read_b128 v[236:239], v126 offset:41984
	s_waitcnt lgkmcnt(3)
	s_setprio 1
	v_mfma_f32_16x16x32_bf16 v[12:15], v[136:139], v[240:243], v[12:15]
	v_mfma_f32_16x16x32_bf16 v[28:31], v[140:143], v[240:243], v[28:31]
	v_mfma_f32_16x16x32_bf16 v[44:47], v[216:219], v[240:243], v[44:47]
	v_mfma_f32_16x16x32_bf16 v[60:63], v[228:231], v[240:243], v[60:63]
	s_setprio 0
	ds_read_b128 v[240:243], v126 offset:43008
	s_waitcnt lgkmcnt(3)
	s_setprio 1
	v_mfma_f32_16x16x32_bf16 v[16:19], v[136:139], v[244:247], v[16:19]
	v_mfma_f32_16x16x32_bf16 v[32:35], v[140:143], v[244:247], v[32:35]
	v_mfma_f32_16x16x32_bf16 v[48:51], v[216:219], v[244:247], v[48:51]
	v_mfma_f32_16x16x32_bf16 v[64:67], v[228:231], v[244:247], v[64:67]
	s_setprio 0
	ds_read_b128 v[244:247], v126 offset:44032
	s_waitcnt lgkmcnt(3)
	s_setprio 1
	v_mfma_f32_16x16x32_bf16 v[68:71], v[136:139], v[232:235], v[68:71]
	v_mfma_f32_16x16x32_bf16 v[84:87], v[140:143], v[232:235], v[84:87]
	v_mfma_f32_16x16x32_bf16 v[100:103], v[216:219], v[232:235], v[100:103]
	v_mfma_f32_16x16x32_bf16 v[116:119], v[228:231], v[232:235], v[116:119]
	s_setprio 0
	s_waitcnt lgkmcnt(2)
	s_setprio 1
	v_mfma_f32_16x16x32_bf16 v[72:75], v[136:139], v[236:239], v[72:75]
	v_mfma_f32_16x16x32_bf16 v[88:91], v[140:143], v[236:239], v[88:91]
	v_mfma_f32_16x16x32_bf16 v[104:107], v[216:219], v[236:239], v[104:107]
	v_mfma_f32_16x16x32_bf16 v[120:123], v[228:231], v[236:239], v[120:123]
	s_setprio 0
	s_waitcnt lgkmcnt(1)
	s_setprio 1
	v_mfma_f32_16x16x32_bf16 v[76:79], v[136:139], v[240:243], v[76:79]
	v_mfma_f32_16x16x32_bf16 v[92:95], v[140:143], v[240:243], v[92:95]
	v_mfma_f32_16x16x32_bf16 v[108:111], v[216:219], v[240:243], v[108:111]
	v_mfma_f32_16x16x32_bf16 v[128:131], v[228:231], v[240:243], v[128:131]
	s_setprio 0
	s_waitcnt lgkmcnt(0)
	s_setprio 1
	v_mfma_f32_16x16x32_bf16 v[80:83], v[136:139], v[244:247], v[80:83]
	v_mfma_f32_16x16x32_bf16 v[96:99], v[140:143], v[244:247], v[96:99]
	v_mfma_f32_16x16x32_bf16 v[112:115], v[216:219], v[244:247], v[112:115]
	v_mfma_f32_16x16x32_bf16 v[132:135], v[228:231], v[244:247], v[132:135]
	s_setprio 0
	s_barrier
	v_and_b32_e32 v214, 15, v196
	v_bfe_u32 v215, v196, 6, 1
	v_lshl_add_u32 v214, v215, 6, v214
	v_mul_u32_u24_e32 v214, 0x110, v214
	v_lshrrev_b32_e32 v215, 7, v196
	v_lshl_add_u32 v214, v215, 7, v214
	v_bfe_u32 v215, v196, 4, 2
	v_lshl_add_u32 v214, v215, 3, v214
	v_lshrrev_b32_e32 v220, 4, v196
	v_and_b32_e32 v0, 15, v196
	v_lshlrev_b32_e32 v0, 4, v0
	v_mad_u32_u24 v215, v220, s30, v0
	s_movk_i32 s2, 0x4200
	v_mad_u32_u24 v227, v220, s2, v0
	s_add_u32 s16, s40, s26
	s_addc_u32 s17, s41, 0
	v_cvt_pk_bf16_f32 v248, v4, v5
	v_cvt_pk_bf16_f32 v249, v6, v7
	ds_write_b64 v214, v[248:249] offset:0
	v_cvt_pk_bf16_f32 v250, v20, v21
	v_cvt_pk_bf16_f32 v251, v22, v23
	ds_write_b64 v214, v[250:251] offset:32
	v_cvt_pk_bf16_f32 v248, v36, v37
	v_cvt_pk_bf16_f32 v249, v38, v39
	ds_write_b64 v214, v[248:249] offset:64
	v_cvt_pk_bf16_f32 v250, v52, v53
	v_cvt_pk_bf16_f32 v251, v54, v55
	ds_write_b64 v214, v[250:251] offset:96
	v_cvt_pk_bf16_f32 v248, v8, v9
	v_cvt_pk_bf16_f32 v249, v10, v11
	ds_write_b64 v214, v[248:249] offset:4352
	v_cvt_pk_bf16_f32 v250, v24, v25
	v_cvt_pk_bf16_f32 v251, v26, v27
	ds_write_b64 v214, v[250:251] offset:4384
	v_cvt_pk_bf16_f32 v248, v40, v41
	v_cvt_pk_bf16_f32 v249, v42, v43
	ds_write_b64 v214, v[248:249] offset:4416
	v_cvt_pk_bf16_f32 v250, v56, v57
	v_cvt_pk_bf16_f32 v251, v58, v59
	ds_write_b64 v214, v[250:251] offset:4448
	v_cvt_pk_bf16_f32 v248, v12, v13
	v_cvt_pk_bf16_f32 v249, v14, v15
	ds_write_b64 v214, v[248:249] offset:8704
	v_cvt_pk_bf16_f32 v250, v28, v29
	v_cvt_pk_bf16_f32 v251, v30, v31
	ds_write_b64 v214, v[250:251] offset:8736
	v_cvt_pk_bf16_f32 v248, v44, v45
	v_cvt_pk_bf16_f32 v249, v46, v47
	ds_write_b64 v214, v[248:249] offset:8768
	v_cvt_pk_bf16_f32 v250, v60, v61
	v_cvt_pk_bf16_f32 v251, v62, v63
	ds_write_b64 v214, v[250:251] offset:8800
	v_cvt_pk_bf16_f32 v248, v16, v17
	v_cvt_pk_bf16_f32 v249, v18, v19
	ds_write_b64 v214, v[248:249] offset:13056
	v_cvt_pk_bf16_f32 v250, v32, v33
	v_cvt_pk_bf16_f32 v251, v34, v35
	ds_write_b64 v214, v[250:251] offset:13088
	v_cvt_pk_bf16_f32 v248, v48, v49
	v_cvt_pk_bf16_f32 v249, v50, v51
	ds_write_b64 v214, v[248:249] offset:13120
	v_cvt_pk_bf16_f32 v250, v64, v65
	v_cvt_pk_bf16_f32 v251, v66, v67
	ds_write_b64 v214, v[250:251] offset:13152
	s_waitcnt lgkmcnt(0)
	s_barrier
	ds_read_b128 v[136:139], v215 offset:0
	ds_read_b128 v[140:143], v215 offset:4352
	ds_read_b128 v[216:219], v215 offset:8704
	ds_read_b128 v[228:231], v215 offset:13056
	ds_read_b128 v[232:235], v215 offset:17408
	ds_read_b128 v[236:239], v215 offset:21760
	ds_read_b128 v[240:243], v215 offset:26112
	ds_read_b128 v[244:247], v215 offset:30464
	v_mov_b32_e32 v220, v227
	s_waitcnt lgkmcnt(7)
	global_store_dwordx4 v220, v[136:139], s[16:17]
	v_add_u32_e32 v220, 0x42000, v220
	s_waitcnt lgkmcnt(6)
	global_store_dwordx4 v220, v[140:143], s[16:17]
	v_add_u32_e32 v220, 0x42000, v220
	s_waitcnt lgkmcnt(5)
	global_store_dwordx4 v220, v[216:219], s[16:17]
	v_add_u32_e32 v220, 0x42000, v220
	s_waitcnt lgkmcnt(4)
	global_store_dwordx4 v220, v[228:231], s[16:17]
	v_add_u32_e32 v220, 0x42000, v220
	s_waitcnt lgkmcnt(3)
	global_store_dwordx4 v220, v[232:235], s[16:17]
	v_add_u32_e32 v220, 0x42000, v220
	s_waitcnt lgkmcnt(2)
	global_store_dwordx4 v220, v[236:239], s[16:17]
	v_add_u32_e32 v220, 0x42000, v220
	s_waitcnt lgkmcnt(1)
	global_store_dwordx4 v220, v[240:243], s[16:17]
	v_add_u32_e32 v220, 0x42000, v220
	s_waitcnt lgkmcnt(0)
	global_store_dwordx4 v220, v[244:247], s[16:17]
	s_barrier
	s_add_u32 s16, s40, s26
	s_addc_u32 s17, s41, 0
	s_add_u32 s16, s16, 0x210000
	s_addc_u32 s17, s17, 0
	v_cvt_pk_bf16_f32 v248, v68, v69
	v_cvt_pk_bf16_f32 v249, v70, v71
	ds_write_b64 v214, v[248:249] offset:0
	v_cvt_pk_bf16_f32 v250, v84, v85
	v_cvt_pk_bf16_f32 v251, v86, v87
	ds_write_b64 v214, v[250:251] offset:32
	v_cvt_pk_bf16_f32 v248, v100, v101
	v_cvt_pk_bf16_f32 v249, v102, v103
	ds_write_b64 v214, v[248:249] offset:64
	v_cvt_pk_bf16_f32 v250, v116, v117
	v_cvt_pk_bf16_f32 v251, v118, v119
	ds_write_b64 v214, v[250:251] offset:96
	v_cvt_pk_bf16_f32 v248, v72, v73
	v_cvt_pk_bf16_f32 v249, v74, v75
	ds_write_b64 v214, v[248:249] offset:4352
	v_cvt_pk_bf16_f32 v250, v88, v89
	v_cvt_pk_bf16_f32 v251, v90, v91
	ds_write_b64 v214, v[250:251] offset:4384
	v_cvt_pk_bf16_f32 v248, v104, v105
	v_cvt_pk_bf16_f32 v249, v106, v107
	ds_write_b64 v214, v[248:249] offset:4416
	v_cvt_pk_bf16_f32 v250, v120, v121
	v_cvt_pk_bf16_f32 v251, v122, v123
	ds_write_b64 v214, v[250:251] offset:4448
	v_cvt_pk_bf16_f32 v248, v76, v77
	v_cvt_pk_bf16_f32 v249, v78, v79
	ds_write_b64 v214, v[248:249] offset:8704
	v_cvt_pk_bf16_f32 v250, v92, v93
	v_cvt_pk_bf16_f32 v251, v94, v95
	ds_write_b64 v214, v[250:251] offset:8736
	v_cvt_pk_bf16_f32 v248, v108, v109
	v_cvt_pk_bf16_f32 v249, v110, v111
	ds_write_b64 v214, v[248:249] offset:8768
	v_cvt_pk_bf16_f32 v250, v128, v129
	v_cvt_pk_bf16_f32 v251, v130, v131
	ds_write_b64 v214, v[250:251] offset:8800
	v_cvt_pk_bf16_f32 v248, v80, v81
	v_cvt_pk_bf16_f32 v249, v82, v83
	ds_write_b64 v214, v[248:249] offset:13056
	v_cvt_pk_bf16_f32 v250, v96, v97
	v_cvt_pk_bf16_f32 v251, v98, v99
	ds_write_b64 v214, v[250:251] offset:13088
	v_cvt_pk_bf16_f32 v248, v112, v113
	v_cvt_pk_bf16_f32 v249, v114, v115
	ds_write_b64 v214, v[248:249] offset:13120
	v_cvt_pk_bf16_f32 v250, v132, v133
	v_cvt_pk_bf16_f32 v251, v134, v135
	ds_write_b64 v214, v[250:251] offset:13152
	s_waitcnt lgkmcnt(0)
	s_barrier
	ds_read_b128 v[136:139], v215 offset:0
	ds_read_b128 v[140:143], v215 offset:4352
	ds_read_b128 v[216:219], v215 offset:8704
	ds_read_b128 v[228:231], v215 offset:13056
	ds_read_b128 v[232:235], v215 offset:17408
	ds_read_b128 v[236:239], v215 offset:21760
	ds_read_b128 v[240:243], v215 offset:26112
	ds_read_b128 v[244:247], v215 offset:30464
	v_mov_b32_e32 v220, v227
	s_waitcnt lgkmcnt(7)
	global_store_dwordx4 v220, v[136:139], s[16:17]
	v_add_u32_e32 v220, 0x42000, v220
	s_waitcnt lgkmcnt(6)
	global_store_dwordx4 v220, v[140:143], s[16:17]
	v_add_u32_e32 v220, 0x42000, v220
	s_waitcnt lgkmcnt(5)
	global_store_dwordx4 v220, v[216:219], s[16:17]
	v_add_u32_e32 v220, 0x42000, v220
	s_waitcnt lgkmcnt(4)
	global_store_dwordx4 v220, v[228:231], s[16:17]
	v_add_u32_e32 v220, 0x42000, v220
	s_waitcnt lgkmcnt(3)
	global_store_dwordx4 v220, v[232:235], s[16:17]
	v_add_u32_e32 v220, 0x42000, v220
	s_waitcnt lgkmcnt(2)
	global_store_dwordx4 v220, v[236:239], s[16:17]
	v_add_u32_e32 v220, 0x42000, v220
	s_waitcnt lgkmcnt(1)
	global_store_dwordx4 v220, v[240:243], s[16:17]
	v_add_u32_e32 v220, 0x42000, v220
	s_waitcnt lgkmcnt(0)
	global_store_dwordx4 v220, v[244:247], s[16:17]
	s_barrier
	s_mov_b64 s[16:17], 0
